# FFN-in: per-row sum-of-squares values prefetched at the top of each tile (before its K-loop) so the epilogue does not start with 8 loads + vmcnt(0)
# speedup vs baseline: 1.0013x; 1.0013x over previous
.LBB0_1126:
	v_lshl_add_u32 v248, s4, 8, v154
	v_ashrrev_i32_e32 v249, 31, v248
	v_lshl_add_u64 v[250:251], v[248:249], 2, s[10:11]
	global_load_dword v240, v[250:251], off
	global_load_dword v242, v[250:251], off offset:512
	global_load_dword v243, v[250:251], off offset:576
	global_load_dword v244, v[250:251], off offset:640
	global_load_dword v247, v[250:251], off offset:704
	v_or_b32_e32 v252, 16, v248
	v_ashrrev_i32_e32 v253, 31, v252
	v_lshl_add_u64 v[252:253], v[252:253], 2, s[10:11]
	global_load_dword v241, v[252:253], off
	v_or_b32_e32 v254, 32, v248
	v_ashrrev_i32_e32 v255, 31, v254
	v_lshl_add_u64 v[254:255], v[254:255], 2, s[10:11]
	global_load_dword v245, v[254:255], off
	v_or_b32_e32 v252, 48, v248
	v_ashrrev_i32_e32 v253, 31, v252
	v_lshl_add_u64 v[252:253], v[252:253], 2, s[10:11]
	global_load_dword v246, v[252:253], off
	s_add_i32 s43, s43, 1
	s_mul_i32 s0, s43, s46
	s_mul_hi_u32 s1, s43, s47
	s_add_i32 s1, s1, s0
	s_mul_i32 s0, s43, s47
	s_add_u32 s22, s0, s2
	s_addc_u32 s23, s1, s37
	v_cmp_gt_i64_e32 vcc, s[22:23], v[142:143]
	v_cmp_lt_i64_e64 s[0:1], s[22:23], v[140:141]
	s_cbranch_vccnz .LBB0_1128
	s_ashr_i32 s18, s22, 31
	s_lshr_b32 s18, s18, 29
	s_add_i32 s18, s22, s18
	s_ashr_i32 s19, s18, 3
	s_and_b32 s18, s18, -8
	s_sub_i32 s18, s22, s18
	s_cmp_lt_i32 s18, 0
	s_cselect_b32 s20, s38, 0x2c0
	s_mul_i32 s18, s18, s20
	s_add_i32 s18, s18, s19
	s_mul_hi_i32 s19, s18, 0x2e8ba2e9
	s_lshr_b32 s20, s19, 31
	s_ashr_i32 s19, s19, 5
	s_add_i32 s19, s19, s20
	s_lshl_b32 s20, s19, 3
	s_sub_i32 s21, 0x100, s20
	s_min_i32 s21, s21, 8
	s_abs_i32 s22, s21
	v_cvt_f32_u32_e32 v0, s22
	s_sub_i32 s24, 0, s22
	s_mulk_i32 s19, 0xb0
	s_sub_i32 s19, s18, s19
	v_rcp_iflag_f32_e32 v0, v0
	s_abs_i32 s18, s19
	s_xor_b32 s23, s19, s21
	s_ashr_i32 s23, s23, 31
	v_mul_f32_e32 v0, 0x4f7ffffe, v0
	v_cvt_u32_f32_e32 v0, v0
	s_nop 0
	v_readfirstlane_b32 s25, v0
	s_mul_i32 s24, s24, s25
	s_mul_hi_u32 s24, s25, s24
	s_add_i32 s25, s25, s24
	s_mul_hi_u32 s24, s18, s25
	s_mul_i32 s25, s24, s22
	s_sub_i32 s18, s18, s25
	s_add_i32 s30, s24, 1
	s_sub_i32 s25, s18, s22
	s_cmp_ge_u32 s18, s22
	s_cselect_b32 s24, s30, s24
	s_cselect_b32 s18, s25, s18
	s_add_i32 s25, s24, 1
	s_cmp_ge_u32 s18, s22
	s_cselect_b32 s18, s25, s24
	s_xor_b32 s18, s18, s23
	s_sub_i32 s18, s18, s23
	s_mul_i32 s21, s18, s21
	s_sub_i32 s19, s19, s21
	s_add_i32 s20, s20, s19

.LBB0_1132:
	v_lshl_add_u32 v146, s4, 8, v154
	v_ashrrev_i32_e32 v147, 31, v146
	v_lshl_add_u64 v[164:165], v[146:147], 2, s[10:11]
	v_or_b32_e32 v150, 16, v146
	v_mov_b32_e32 v163, v240
	v_ashrrev_i32_e32 v151, 31, v150
	v_lshl_add_u64 v[144:145], v[150:151], 2, s[10:11]
	v_mov_b32_e32 v172, v241
	v_lshl_or_b32 v166, s5, 7, v156
	v_or_b32_e32 v152, 32, v146
	v_mov_b64_e32 v[144:145], s[12:13]
	v_or_b32_e32 v148, 48, v146
	v_ashrrev_i32_e32 v167, 31, v166
	v_ashrrev_i32_e32 v153, 31, v152
	v_add_u32_e32 v178, 0x80, v146
	v_add_u32_e32 v162, 0x90, v146
	v_add_u32_e32 v161, 0xa0, v146
	v_add_u32_e32 v151, 0xb0, v146
	v_mad_i64_i32 v[168:169], s[4:5], v146, s51, v[144:145]
	v_ashrrev_i32_e32 v149, 31, v148
	v_lshlrev_b64 v[146:147], 1, v[166:167]
	v_lshl_add_u64 v[166:167], v[152:153], 2, s[10:11]
	v_lshl_add_u64 v[170:171], v[148:149], 2, s[10:11]
	v_mov_b32_e32 v179, v242
	v_mov_b32_e32 v180, v243
	v_mov_b32_e32 v153, v244
	s_nop 0
	v_mov_b32_e32 v167, v245
	s_nop 0
	v_mov_b32_e32 v181, v246
	v_mov_b32_e32 v149, v247
	v_fmamk_f32 v163, v163, 0x3a800000, v160
	v_mul_f32_e32 v164, 0x4b800000, v163
	v_cmp_gt_f32_e32 vcc, s50, v163
	v_fmamk_f32 v165, v172, 0x3a800000, v160
	v_cmp_gt_f32_e64 s[4:5], s50, v165
	v_cndmask_b32_e32 v163, v163, v164, vcc
	v_mul_f32_e32 v164, 0x4b800000, v165
	v_rsq_f32_e32 v163, v163
	v_cndmask_b32_e64 v164, v165, v164, s[4:5]
	v_rsq_f32_e32 v170, v164
	v_lshl_add_u64 v[164:165], v[168:169], 0, v[146:147]
	v_mul_f32_e32 v166, 0x45800000, v163
	v_cndmask_b32_e32 v166, v163, v166, vcc
	v_mul_f32_e32 v163, 0x45800000, v170
	v_pk_mul_f32 v[124:125], v[124:125], v[166:167] op_sel_hi:[1,0]
	v_pk_mul_f32 v[126:127], v[126:127], v[166:167] op_sel_hi:[1,0]
	v_pk_mul_f32 v[120:121], v[120:121], v[166:167] op_sel_hi:[1,0]
	v_pk_mul_f32 v[122:123], v[122:123], v[166:167] op_sel_hi:[1,0]
	v_pk_mul_f32 v[116:117], v[116:117], v[166:167] op_sel_hi:[1,0]
	v_pk_mul_f32 v[118:119], v[118:119], v[166:167] op_sel_hi:[1,0]
	v_pk_mul_f32 v[112:113], v[112:113], v[166:167] op_sel_hi:[1,0]
	v_pk_mul_f32 v[114:115], v[114:115], v[166:167] op_sel_hi:[1,0]
	v_cndmask_b32_e64 v166, v170, v163, s[4:5]
	v_mul_f32_e32 v163, 0xbfb8aa3b, v124
	v_mul_f32_e32 v168, 0xbfb8aa3b, v125
	v_mul_f32_e32 v169, 0xbfb8aa3b, v126
	v_mul_f32_e32 v170, 0xbfb8aa3b, v127
	v_mul_f32_e32 v171, 0xbfb8aa3b, v120
	v_mul_f32_e32 v172, 0xbfb8aa3b, v121
	v_mul_f32_e32 v173, 0xbfb8aa3b, v122
	v_mul_f32_e32 v174, 0xbfb8aa3b, v123
	v_exp_f32_e32 v163, v163
	v_exp_f32_e32 v168, v168
	v_exp_f32_e32 v169, v169
	v_exp_f32_e32 v170, v170
	v_exp_f32_e32 v171, v171
	v_exp_f32_e32 v172, v172
	v_exp_f32_e32 v173, v173
	v_exp_f32_e32 v174, v174
	v_pk_mul_f32 v[108:109], v[108:109], v[166:167] op_sel_hi:[1,0]
	v_add_f32_e32 v163, 1.0, v163
	v_mul_f32_e32 v175, 0xbfb8aa3b, v108
	v_exp_f32_e32 v177, v175
	v_add_f32_e32 v175, 1.0, v168
	v_add_f32_e32 v182, 1.0, v169
	v_add_f32_e32 v183, 1.0, v170
	v_add_f32_e32 v184, 1.0, v171
	v_add_f32_e32 v185, 1.0, v172
	v_add_f32_e32 v186, 1.0, v173
	v_add_f32_e32 v187, 1.0, v174
	v_rcp_f32_e32 v168, v163
	v_rcp_f32_e32 v169, v175
	v_rcp_f32_e32 v170, v182
	v_rcp_f32_e32 v171, v183
	v_rcp_f32_e32 v172, v184
	v_rcp_f32_e32 v173, v185
	v_rcp_f32_e32 v174, v186
	v_rcp_f32_e32 v175, v187
	v_pk_mul_f32 v[124:125], v[124:125], v[168:169]
	v_pk_mul_f32 v[126:127], v[126:127], v[170:171]
	v_pk_mul_f32 v[120:121], v[120:121], v[172:173]
	v_pk_mul_f32 v[122:123], v[122:123], v[174:175]
	v_pk_mul_f32 v[116:117], v[116:117], v[124:125]
	v_pk_mul_f32 v[118:119], v[118:119], v[126:127]
	v_pk_mul_f32 v[120:121], v[112:113], v[120:121]
	v_pk_mul_f32 v[122:123], v[114:115], v[122:123]
	v_mul_f32_e32 v176, 0xbfb8aa3b, v109
	v_cvt_pk_bf16_f32 v112, v116, v117
	v_cvt_pk_bf16_f32 v113, v118, v119
	v_cvt_pk_bf16_f32 v114, v120, v121
	v_cvt_pk_bf16_f32 v115, v122, v123
	v_pk_mul_f32 v[110:111], v[110:111], v[166:167] op_sel_hi:[1,0]
	v_exp_f32_e32 v176, v176
	global_store_dwordx4 v[164:165], v[112:115], off
	v_add_f32_e32 v163, 1.0, v177
	v_pk_mul_f32 v[100:101], v[100:101], v[166:167] op_sel_hi:[1,0]
	v_mul_f32_e32 v112, 0xbfb8aa3b, v110
	v_mul_f32_e32 v113, 0xbfb8aa3b, v111
	v_exp_f32_e32 v112, v112
	v_exp_f32_e32 v113, v113
	v_add_f32_e32 v177, 1.0, v176
	v_rcp_f32_e32 v176, v163
	v_rcp_f32_e32 v177, v177
	v_add_f32_e32 v112, 1.0, v112
	v_add_f32_e32 v113, 1.0, v113
	v_rcp_f32_e32 v112, v112
	v_rcp_f32_e32 v113, v113
	v_pk_mul_f32 v[108:109], v[108:109], v[176:177]
	v_pk_mul_f32 v[104:105], v[104:105], v[166:167] op_sel_hi:[1,0]
	v_pk_mul_f32 v[100:101], v[100:101], v[108:109]
	v_pk_mul_f32 v[108:109], v[110:111], v[112:113]
	v_mul_f32_e32 v110, 0xbfb8aa3b, v104
	v_exp_f32_e32 v110, v110
	v_pk_mul_f32 v[102:103], v[102:103], v[166:167] op_sel_hi:[1,0]
	v_pk_mul_f32 v[106:107], v[106:107], v[166:167] op_sel_hi:[1,0]
	v_pk_mul_f32 v[102:103], v[102:103], v[108:109]
	v_mul_f32_e32 v108, 0xbfb8aa3b, v105
	v_exp_f32_e32 v109, v108
	v_add_f32_e32 v108, 1.0, v110
	v_mul_f32_e32 v110, 0xbfb8aa3b, v106
	v_mul_f32_e32 v111, 0xbfb8aa3b, v107
	v_exp_f32_e32 v110, v110
	v_exp_f32_e32 v111, v111
	v_add_f32_e32 v109, 1.0, v109
	v_rcp_f32_e32 v108, v108
	v_rcp_f32_e32 v109, v109
	v_add_f32_e32 v110, 1.0, v110
	v_add_f32_e32 v111, 1.0, v111
	v_rcp_f32_e32 v110, v110
	v_rcp_f32_e32 v111, v111
	v_pk_mul_f32 v[96:97], v[96:97], v[166:167] op_sel_hi:[1,0]
	v_pk_mul_f32 v[104:105], v[104:105], v[108:109]
	s_nop 0
	v_pk_mul_f32 v[104:105], v[96:97], v[104:105]
	v_pk_mul_f32 v[96:97], v[98:99], v[166:167] op_sel_hi:[1,0]
	v_pk_mul_f32 v[98:99], v[106:107], v[110:111]
	s_nop 0
	v_pk_mul_f32 v[106:107], v[96:97], v[98:99]
	v_cvt_pk_bf16_f32 v96, v100, v101
	v_fmamk_f32 v100, v167, 0x3a800000, v160
	v_mul_f32_e32 v101, 0x4b800000, v100
	v_cmp_gt_f32_e32 vcc, s50, v100
	v_cvt_pk_bf16_f32 v97, v102, v103
	v_cvt_pk_bf16_f32 v98, v104, v105
	v_cndmask_b32_e32 v100, v100, v101, vcc
	v_rsq_f32_e32 v102, v100
	v_mad_i64_i32 v[100:101], s[4:5], v150, s51, v[144:145]
	v_cvt_pk_bf16_f32 v99, v106, v107
	v_mul_f32_e32 v103, 0x45800000, v102
	v_cndmask_b32_e32 v102, v102, v103, vcc
	v_pk_mul_f32 v[92:93], v[92:93], v[102:103] op_sel_hi:[1,0]
	v_lshl_add_u64 v[100:101], v[100:101], 0, v[146:147]
	v_mul_f32_e32 v103, 0xbfb8aa3b, v92
	v_exp_f32_e32 v103, v103
	global_store_dwordx4 v[100:101], v[96:99], off
	v_pk_mul_f32 v[94:95], v[94:95], v[102:103] op_sel_hi:[1,0]
	s_nop 0
	v_mul_f32_e32 v96, 0xbfb8aa3b, v93
	v_exp_f32_e32 v97, v96
	v_mul_f32_e32 v98, 0xbfb8aa3b, v94
	v_mul_f32_e32 v99, 0xbfb8aa3b, v95
	v_exp_f32_e32 v98, v98
	v_exp_f32_e32 v99, v99
	v_add_f32_e32 v96, 1.0, v103
	v_add_f32_e32 v97, 1.0, v97
	v_rcp_f32_e32 v96, v96
	v_rcp_f32_e32 v97, v97
	v_add_f32_e32 v98, 1.0, v98
	v_add_f32_e32 v99, 1.0, v99
	v_rcp_f32_e32 v98, v98
	v_rcp_f32_e32 v99, v99
	v_pk_mul_f32 v[84:85], v[84:85], v[102:103] op_sel_hi:[1,0]
	v_pk_mul_f32 v[92:93], v[92:93], v[96:97]
	v_pk_mul_f32 v[88:89], v[88:89], v[102:103] op_sel_hi:[1,0]
	v_pk_mul_f32 v[84:85], v[84:85], v[92:93]
	v_pk_mul_f32 v[92:93], v[94:95], v[98:99]
	v_mul_f32_e32 v94, 0xbfb8aa3b, v88
	v_exp_f32_e32 v94, v94
	v_pk_mul_f32 v[86:87], v[86:87], v[102:103] op_sel_hi:[1,0]
	v_pk_mul_f32 v[90:91], v[90:91], v[102:103] op_sel_hi:[1,0]
	v_pk_mul_f32 v[86:87], v[86:87], v[92:93]
	v_mul_f32_e32 v92, 0xbfb8aa3b, v89
	v_exp_f32_e32 v93, v92
	v_add_f32_e32 v92, 1.0, v94
	v_mul_f32_e32 v94, 0xbfb8aa3b, v90
	v_mul_f32_e32 v95, 0xbfb8aa3b, v91
	v_exp_f32_e32 v94, v94
	v_exp_f32_e32 v95, v95
	v_add_f32_e32 v93, 1.0, v93
	v_rcp_f32_e32 v92, v92
	v_rcp_f32_e32 v93, v93
	v_add_f32_e32 v94, 1.0, v94
	v_add_f32_e32 v95, 1.0, v95
	v_rcp_f32_e32 v94, v94
	v_rcp_f32_e32 v95, v95
	v_pk_mul_f32 v[80:81], v[80:81], v[102:103] op_sel_hi:[1,0]
	v_pk_mul_f32 v[88:89], v[88:89], v[92:93]
	s_nop 0
	v_pk_mul_f32 v[88:89], v[80:81], v[88:89]
	v_pk_mul_f32 v[80:81], v[82:83], v[102:103] op_sel_hi:[1,0]
	v_pk_mul_f32 v[82:83], v[90:91], v[94:95]
	s_nop 0
	v_pk_mul_f32 v[90:91], v[80:81], v[82:83]
	v_cvt_pk_bf16_f32 v80, v84, v85
	v_fmamk_f32 v84, v181, 0x3a800000, v160
	v_mul_f32_e32 v85, 0x4b800000, v84
	v_cmp_gt_f32_e32 vcc, s50, v84
	v_cvt_pk_bf16_f32 v81, v86, v87
	v_cvt_pk_bf16_f32 v82, v88, v89
	v_cndmask_b32_e32 v84, v84, v85, vcc
	v_rsq_f32_e32 v86, v84
	v_mad_i64_i32 v[84:85], s[4:5], v152, s51, v[144:145]
	v_cvt_pk_bf16_f32 v83, v90, v91
	v_mul_f32_e32 v87, 0x45800000, v86
	v_cndmask_b32_e32 v86, v86, v87, vcc
	v_pk_mul_f32 v[76:77], v[76:77], v[86:87] op_sel_hi:[1,0]
	v_lshl_add_u64 v[84:85], v[84:85], 0, v[146:147]
	v_mul_f32_e32 v87, 0xbfb8aa3b, v76
	v_exp_f32_e32 v87, v87
	global_store_dwordx4 v[84:85], v[80:83], off
	v_pk_mul_f32 v[78:79], v[78:79], v[86:87] op_sel_hi:[1,0]
	s_nop 0
	v_mul_f32_e32 v80, 0xbfb8aa3b, v77
	v_exp_f32_e32 v81, v80
	v_mul_f32_e32 v82, 0xbfb8aa3b, v78
	v_mul_f32_e32 v83, 0xbfb8aa3b, v79
	v_exp_f32_e32 v82, v82
	v_exp_f32_e32 v83, v83
	v_add_f32_e32 v80, 1.0, v87
	v_add_f32_e32 v81, 1.0, v81
	v_rcp_f32_e32 v80, v80
	v_rcp_f32_e32 v81, v81
	v_add_f32_e32 v82, 1.0, v82
	v_add_f32_e32 v83, 1.0, v83
	v_rcp_f32_e32 v82, v82
	v_rcp_f32_e32 v83, v83
	v_pk_mul_f32 v[68:69], v[68:69], v[86:87] op_sel_hi:[1,0]
	v_pk_mul_f32 v[76:77], v[76:77], v[80:81]
	v_pk_mul_f32 v[72:73], v[72:73], v[86:87] op_sel_hi:[1,0]
	v_pk_mul_f32 v[68:69], v[68:69], v[76:77]
	v_pk_mul_f32 v[76:77], v[78:79], v[82:83]
	v_mul_f32_e32 v78, 0xbfb8aa3b, v72
	v_exp_f32_e32 v78, v78
	v_pk_mul_f32 v[70:71], v[70:71], v[86:87] op_sel_hi:[1,0]
	v_pk_mul_f32 v[74:75], v[74:75], v[86:87] op_sel_hi:[1,0]
	v_pk_mul_f32 v[70:71], v[70:71], v[76:77]
	v_mul_f32_e32 v76, 0xbfb8aa3b, v73
	v_exp_f32_e32 v77, v76
	v_add_f32_e32 v76, 1.0, v78
	v_mul_f32_e32 v78, 0xbfb8aa3b, v74
	v_mul_f32_e32 v79, 0xbfb8aa3b, v75
	v_exp_f32_e32 v78, v78
	v_exp_f32_e32 v79, v79
	v_add_f32_e32 v77, 1.0, v77
	v_rcp_f32_e32 v76, v76
	v_rcp_f32_e32 v77, v77
	v_add_f32_e32 v78, 1.0, v78
	v_add_f32_e32 v79, 1.0, v79
	v_rcp_f32_e32 v78, v78
	v_rcp_f32_e32 v79, v79
	v_pk_mul_f32 v[64:65], v[64:65], v[86:87] op_sel_hi:[1,0]
	v_pk_mul_f32 v[72:73], v[72:73], v[76:77]
	s_nop 0
	v_pk_mul_f32 v[72:73], v[64:65], v[72:73]
	v_pk_mul_f32 v[64:65], v[66:67], v[86:87] op_sel_hi:[1,0]
	v_pk_mul_f32 v[66:67], v[74:75], v[78:79]
	s_nop 0
	v_pk_mul_f32 v[74:75], v[64:65], v[66:67]
	v_cvt_pk_bf16_f32 v64, v68, v69
	v_fmamk_f32 v68, v179, 0x3a800000, v160
	v_mul_f32_e32 v69, 0x4b800000, v68
	v_cmp_gt_f32_e32 vcc, s50, v68
	v_cvt_pk_bf16_f32 v65, v70, v71
	v_cvt_pk_bf16_f32 v66, v72, v73
	v_cndmask_b32_e32 v68, v68, v69, vcc
	v_rsq_f32_e32 v70, v68
	v_mad_i64_i32 v[68:69], s[4:5], v148, s51, v[144:145]
	v_cvt_pk_bf16_f32 v67, v74, v75
	v_mul_f32_e32 v71, 0x45800000, v70
	v_cndmask_b32_e32 v70, v70, v71, vcc
	v_pk_mul_f32 v[60:61], v[60:61], v[70:71] op_sel_hi:[1,0]
	v_lshl_add_u64 v[68:69], v[68:69], 0, v[146:147]
	v_mul_f32_e32 v71, 0xbfb8aa3b, v60
	v_exp_f32_e32 v71, v71
	global_store_dwordx4 v[68:69], v[64:67], off
	v_pk_mul_f32 v[62:63], v[62:63], v[70:71] op_sel_hi:[1,0]
	s_nop 0
	v_mul_f32_e32 v64, 0xbfb8aa3b, v61
	v_exp_f32_e32 v65, v64
	v_mul_f32_e32 v66, 0xbfb8aa3b, v62
	v_mul_f32_e32 v67, 0xbfb8aa3b, v63
	v_exp_f32_e32 v66, v66
	v_exp_f32_e32 v67, v67
	v_add_f32_e32 v64, 1.0, v71
	v_add_f32_e32 v65, 1.0, v65
	v_rcp_f32_e32 v64, v64
	v_rcp_f32_e32 v65, v65
	v_add_f32_e32 v66, 1.0, v66
	v_add_f32_e32 v67, 1.0, v67
	v_rcp_f32_e32 v66, v66
	v_rcp_f32_e32 v67, v67
	v_pk_mul_f32 v[52:53], v[52:53], v[70:71] op_sel_hi:[1,0]
	v_pk_mul_f32 v[60:61], v[60:61], v[64:65]
	v_pk_mul_f32 v[56:57], v[56:57], v[70:71] op_sel_hi:[1,0]
	v_pk_mul_f32 v[52:53], v[52:53], v[60:61]
	v_pk_mul_f32 v[60:61], v[62:63], v[66:67]
	v_mul_f32_e32 v62, 0xbfb8aa3b, v56
	v_exp_f32_e32 v62, v62
	v_pk_mul_f32 v[54:55], v[54:55], v[70:71] op_sel_hi:[1,0]
	v_pk_mul_f32 v[58:59], v[58:59], v[70:71] op_sel_hi:[1,0]
	v_pk_mul_f32 v[54:55], v[54:55], v[60:61]
	v_mul_f32_e32 v60, 0xbfb8aa3b, v57
	v_exp_f32_e32 v61, v60
	v_add_f32_e32 v60, 1.0, v62
	v_mul_f32_e32 v62, 0xbfb8aa3b, v58
	v_mul_f32_e32 v63, 0xbfb8aa3b, v59
	v_exp_f32_e32 v62, v62
	v_exp_f32_e32 v63, v63
	v_add_f32_e32 v61, 1.0, v61
	v_rcp_f32_e32 v60, v60
	v_rcp_f32_e32 v61, v61
	v_add_f32_e32 v62, 1.0, v62
	v_add_f32_e32 v63, 1.0, v63
	v_rcp_f32_e32 v62, v62
	v_rcp_f32_e32 v63, v63
	v_pk_mul_f32 v[48:49], v[48:49], v[70:71] op_sel_hi:[1,0]
	v_pk_mul_f32 v[56:57], v[56:57], v[60:61]
	s_nop 0
	v_pk_mul_f32 v[56:57], v[48:49], v[56:57]
	v_pk_mul_f32 v[48:49], v[50:51], v[70:71] op_sel_hi:[1,0]
	v_pk_mul_f32 v[50:51], v[58:59], v[62:63]
	s_nop 0
	v_pk_mul_f32 v[58:59], v[48:49], v[50:51]
	v_cvt_pk_bf16_f32 v48, v52, v53
	v_fmamk_f32 v52, v180, 0x3a800000, v160
	v_mul_f32_e32 v53, 0x4b800000, v52
	v_cmp_gt_f32_e32 vcc, s50, v52
	v_cvt_pk_bf16_f32 v49, v54, v55
	v_cvt_pk_bf16_f32 v50, v56, v57
	v_cndmask_b32_e32 v52, v52, v53, vcc
	v_rsq_f32_e32 v54, v52
	v_mad_i64_i32 v[52:53], s[4:5], v178, s51, v[144:145]
	v_cvt_pk_bf16_f32 v51, v58, v59
	v_mul_f32_e32 v55, 0x45800000, v54
	v_cndmask_b32_e32 v54, v54, v55, vcc
	v_pk_mul_f32 v[44:45], v[44:45], v[54:55] op_sel_hi:[1,0]
	v_lshl_add_u64 v[52:53], v[52:53], 0, v[146:147]
	v_mul_f32_e32 v55, 0xbfb8aa3b, v44
	v_exp_f32_e32 v55, v55
	global_store_dwordx4 v[52:53], v[48:51], off
	v_pk_mul_f32 v[46:47], v[46:47], v[54:55] op_sel_hi:[1,0]
	s_nop 0
	v_mul_f32_e32 v48, 0xbfb8aa3b, v45
	v_exp_f32_e32 v49, v48
	v_mul_f32_e32 v50, 0xbfb8aa3b, v46
	v_mul_f32_e32 v51, 0xbfb8aa3b, v47
	v_exp_f32_e32 v50, v50
	v_exp_f32_e32 v51, v51
	v_add_f32_e32 v48, 1.0, v55
	v_add_f32_e32 v49, 1.0, v49
	v_rcp_f32_e32 v48, v48
	v_rcp_f32_e32 v49, v49
	v_add_f32_e32 v50, 1.0, v50
	v_add_f32_e32 v51, 1.0, v51
	v_rcp_f32_e32 v50, v50
	v_rcp_f32_e32 v51, v51
	v_pk_mul_f32 v[36:37], v[36:37], v[54:55] op_sel_hi:[1,0]
	v_pk_mul_f32 v[44:45], v[44:45], v[48:49]
	v_pk_mul_f32 v[40:41], v[40:41], v[54:55] op_sel_hi:[1,0]
	v_pk_mul_f32 v[36:37], v[36:37], v[44:45]
	v_pk_mul_f32 v[44:45], v[46:47], v[50:51]
	v_mul_f32_e32 v46, 0xbfb8aa3b, v40
	v_exp_f32_e32 v46, v46
	v_pk_mul_f32 v[38:39], v[38:39], v[54:55] op_sel_hi:[1,0]
	v_pk_mul_f32 v[42:43], v[42:43], v[54:55] op_sel_hi:[1,0]
	v_pk_mul_f32 v[38:39], v[38:39], v[44:45]
	v_mul_f32_e32 v44, 0xbfb8aa3b, v41
	v_exp_f32_e32 v45, v44
	v_add_f32_e32 v44, 1.0, v46
	v_mul_f32_e32 v46, 0xbfb8aa3b, v42
	v_mul_f32_e32 v47, 0xbfb8aa3b, v43
	v_exp_f32_e32 v46, v46
	v_exp_f32_e32 v47, v47
	v_add_f32_e32 v45, 1.0, v45
	v_rcp_f32_e32 v44, v44
	v_rcp_f32_e32 v45, v45
	v_add_f32_e32 v46, 1.0, v46
	v_add_f32_e32 v47, 1.0, v47
	v_rcp_f32_e32 v46, v46
	v_rcp_f32_e32 v47, v47
	v_pk_mul_f32 v[32:33], v[32:33], v[54:55] op_sel_hi:[1,0]
	v_pk_mul_f32 v[40:41], v[40:41], v[44:45]
	s_nop 0
	v_pk_mul_f32 v[40:41], v[32:33], v[40:41]
	v_pk_mul_f32 v[32:33], v[34:35], v[54:55] op_sel_hi:[1,0]
	v_pk_mul_f32 v[34:35], v[42:43], v[46:47]
	s_nop 0
	v_pk_mul_f32 v[42:43], v[32:33], v[34:35]
	v_cvt_pk_bf16_f32 v32, v36, v37
	v_fmamk_f32 v36, v153, 0x3a800000, v160
	v_mul_f32_e32 v37, 0x4b800000, v36
	v_cmp_gt_f32_e32 vcc, s50, v36
	v_cvt_pk_bf16_f32 v33, v38, v39
	v_cvt_pk_bf16_f32 v34, v40, v41
	v_cndmask_b32_e32 v36, v36, v37, vcc
	v_rsq_f32_e32 v38, v36
	v_mad_i64_i32 v[36:37], s[4:5], v162, s51, v[144:145]
	v_cvt_pk_bf16_f32 v35, v42, v43
	v_mul_f32_e32 v39, 0x45800000, v38
	v_cndmask_b32_e32 v38, v38, v39, vcc
	v_pk_mul_f32 v[28:29], v[28:29], v[38:39] op_sel_hi:[1,0]
	v_lshl_add_u64 v[36:37], v[36:37], 0, v[146:147]
	v_mul_f32_e32 v39, 0xbfb8aa3b, v28
	v_exp_f32_e32 v39, v39
	global_store_dwordx4 v[36:37], v[32:35], off
	v_pk_mul_f32 v[30:31], v[30:31], v[38:39] op_sel_hi:[1,0]
	s_nop 0
	v_mul_f32_e32 v32, 0xbfb8aa3b, v29
	v_exp_f32_e32 v33, v32
	v_mul_f32_e32 v34, 0xbfb8aa3b, v30
	v_mul_f32_e32 v35, 0xbfb8aa3b, v31
	v_exp_f32_e32 v34, v34
	v_exp_f32_e32 v35, v35
	v_add_f32_e32 v32, 1.0, v39
	v_add_f32_e32 v33, 1.0, v33
	v_rcp_f32_e32 v32, v32
	v_rcp_f32_e32 v33, v33
	v_add_f32_e32 v34, 1.0, v34
	v_add_f32_e32 v35, 1.0, v35
	v_rcp_f32_e32 v34, v34
	v_rcp_f32_e32 v35, v35
	v_pk_mul_f32 v[20:21], v[20:21], v[38:39] op_sel_hi:[1,0]
	v_pk_mul_f32 v[28:29], v[28:29], v[32:33]
	v_pk_mul_f32 v[24:25], v[24:25], v[38:39] op_sel_hi:[1,0]
	v_pk_mul_f32 v[20:21], v[20:21], v[28:29]
	v_pk_mul_f32 v[28:29], v[30:31], v[34:35]
	v_mul_f32_e32 v30, 0xbfb8aa3b, v24
	v_exp_f32_e32 v30, v30
	v_pk_mul_f32 v[22:23], v[22:23], v[38:39] op_sel_hi:[1,0]
	v_pk_mul_f32 v[26:27], v[26:27], v[38:39] op_sel_hi:[1,0]
	v_pk_mul_f32 v[22:23], v[22:23], v[28:29]
	v_mul_f32_e32 v28, 0xbfb8aa3b, v25
	v_exp_f32_e32 v29, v28
	v_add_f32_e32 v28, 1.0, v30
	v_mul_f32_e32 v30, 0xbfb8aa3b, v26
	v_mul_f32_e32 v31, 0xbfb8aa3b, v27
	v_exp_f32_e32 v30, v30
	v_exp_f32_e32 v31, v31
	v_add_f32_e32 v29, 1.0, v29
	v_rcp_f32_e32 v28, v28
	v_rcp_f32_e32 v29, v29
	v_add_f32_e32 v30, 1.0, v30
	v_add_f32_e32 v31, 1.0, v31
	v_rcp_f32_e32 v30, v30
	v_rcp_f32_e32 v31, v31
	v_pk_mul_f32 v[16:17], v[16:17], v[38:39] op_sel_hi:[1,0]
	v_pk_mul_f32 v[24:25], v[24:25], v[28:29]
	s_nop 0
	v_pk_mul_f32 v[24:25], v[16:17], v[24:25]
	v_pk_mul_f32 v[16:17], v[18:19], v[38:39] op_sel_hi:[1,0]
	v_pk_mul_f32 v[18:19], v[26:27], v[30:31]
	s_nop 0
	v_pk_mul_f32 v[26:27], v[16:17], v[18:19]
	v_cvt_pk_bf16_f32 v16, v20, v21
	v_fmamk_f32 v20, v149, 0x3a800000, v160
	v_mul_f32_e32 v21, 0x4b800000, v20
	v_cmp_gt_f32_e32 vcc, s50, v20
	v_cvt_pk_bf16_f32 v17, v22, v23
	v_cvt_pk_bf16_f32 v18, v24, v25
	v_cndmask_b32_e32 v20, v20, v21, vcc
	v_rsq_f32_e32 v22, v20
	v_mad_i64_i32 v[20:21], s[4:5], v161, s51, v[144:145]
	v_cvt_pk_bf16_f32 v19, v26, v27
	v_mul_f32_e32 v23, 0x45800000, v22
	v_cndmask_b32_e32 v22, v22, v23, vcc
	v_pk_mul_f32 v[12:13], v[12:13], v[22:23] op_sel_hi:[1,0]
	v_lshl_add_u64 v[20:21], v[20:21], 0, v[146:147]
	v_mul_f32_e32 v23, 0xbfb8aa3b, v12
	v_exp_f32_e32 v23, v23
	global_store_dwordx4 v[20:21], v[16:19], off
	s_andn2_b64 vcc, exec, s[0:1]
	s_mov_b64 s[0:1], -1
	v_mul_f32_e32 v16, 0xbfb8aa3b, v13
	v_pk_mul_f32 v[14:15], v[14:15], v[22:23] op_sel_hi:[1,0]
	v_exp_f32_e32 v17, v16
	v_mul_f32_e32 v18, 0xbfb8aa3b, v14
	v_mul_f32_e32 v19, 0xbfb8aa3b, v15
	v_exp_f32_e32 v18, v18
	v_exp_f32_e32 v19, v19
	v_add_f32_e32 v16, 1.0, v23
	v_add_f32_e32 v17, 1.0, v17
	v_rcp_f32_e32 v16, v16
	v_rcp_f32_e32 v17, v17
	v_add_f32_e32 v18, 1.0, v18
	v_add_f32_e32 v19, 1.0, v19
	v_rcp_f32_e32 v18, v18
	v_rcp_f32_e32 v19, v19
	v_pk_mul_f32 v[4:5], v[4:5], v[22:23] op_sel_hi:[1,0]
	v_pk_mul_f32 v[12:13], v[12:13], v[16:17]
	v_pk_mul_f32 v[8:9], v[8:9], v[22:23] op_sel_hi:[1,0]
	v_pk_mul_f32 v[4:5], v[4:5], v[12:13]
	v_pk_mul_f32 v[12:13], v[14:15], v[18:19]
	v_mul_f32_e32 v14, 0xbfb8aa3b, v8
	v_exp_f32_e32 v14, v14
	v_pk_mul_f32 v[6:7], v[6:7], v[22:23] op_sel_hi:[1,0]
	v_pk_mul_f32 v[10:11], v[10:11], v[22:23] op_sel_hi:[1,0]
	v_pk_mul_f32 v[6:7], v[6:7], v[12:13]
	v_mul_f32_e32 v12, 0xbfb8aa3b, v9
	v_exp_f32_e32 v13, v12
	v_add_f32_e32 v12, 1.0, v14
	v_mul_f32_e32 v14, 0xbfb8aa3b, v10
	v_mul_f32_e32 v15, 0xbfb8aa3b, v11
	v_exp_f32_e32 v14, v14
	v_exp_f32_e32 v15, v15
	v_add_f32_e32 v13, 1.0, v13
	v_rcp_f32_e32 v12, v12
	v_rcp_f32_e32 v13, v13
	v_add_f32_e32 v14, 1.0, v14
	v_add_f32_e32 v15, 1.0, v15
	v_rcp_f32_e32 v14, v14
	v_rcp_f32_e32 v15, v15
	v_pk_mul_f32 v[0:1], v[0:1], v[22:23] op_sel_hi:[1,0]
	v_pk_mul_f32 v[8:9], v[8:9], v[12:13]
	s_nop 0
	v_pk_mul_f32 v[8:9], v[0:1], v[8:9]
	v_pk_mul_f32 v[0:1], v[2:3], v[22:23] op_sel_hi:[1,0]
	v_pk_mul_f32 v[2:3], v[10:11], v[14:15]
	s_nop 0
	v_pk_mul_f32 v[10:11], v[0:1], v[2:3]
	v_cvt_pk_bf16_f32 v0, v4, v5
	v_mad_i64_i32 v[4:5], s[4:5], v151, s51, v[144:145]
	v_cvt_pk_bf16_f32 v1, v6, v7
	v_cvt_pk_bf16_f32 v2, v8, v9
	v_cvt_pk_bf16_f32 v3, v10, v11
	v_lshl_add_u64 v[4:5], v[4:5], 0, v[146:147]
	global_store_dwordx4 v[4:5], v[0:3], off
	s_cbranch_vccnz .LBB0_1125
	s_andn2_b64 vcc, exec, s[8:9]
	s_cbranch_vccnz .LBB0_1124
	s_barrier
	s_branch .LBB0_1124
